# sum-triggered post-tile rescale also in the SWA and NSA-window attention loops (row-max chain only on first tile)
# baseline (speedup 1.0000x reference)
.LBB0_2142:
	s_addk_i32 s3, 0x5f
	s_bfe_u32 s10, s26, 0x60006
	s_lshr_b32 s3, s3, 6
	s_add_i32 s10, s10, 1
	s_min_u32 s35, s3, s10
	s_sub_i32 s10, 0, s2
	s_lshr_b32 s2, s21, 6
	s_add_i32 s2, s2, 1
	s_min_u32 s2, s2, s8
	s_max_u32 s11, s2, s9
	s_cmp_le_u32 s2, s9
	s_cbranch_scc1 .LBB0_2151
	v_bfe_u32 v0, v2, 5, 1
	v_lshlrev_b32_e32 v107, 2, v0
	v_lshrrev_b32_e32 v4, 2, v2
	v_and_b32_e32 v3, 31, v2
	v_and_or_b32 v4, v4, 3, v107
	v_and_b32_e32 v32, 16, v2
	v_lshlrev_b32_e32 v2, 2, v2
	v_or_b32_e32 v106, s21, v3
	v_and_b32_e32 v33, 12, v2
	v_mul_u32_u24_e32 v34, 0x48, v3
	v_mul_u32_u24_e32 v109, 0xc0, v4
	v_mov_b32_e32 v2, v1
	v_mov_b32_e32 v3, v1
	v_mov_b32_e32 v4, v1
	v_mov_b32_e32 v5, v1
	v_mov_b32_e32 v6, v1
	v_mov_b32_e32 v7, v1
	v_mov_b32_e32 v8, v1
	v_mov_b32_e32 v9, v1
	v_mov_b32_e32 v10, v1
	v_mov_b32_e32 v11, v1
	v_mov_b32_e32 v12, v1
	v_mov_b32_e32 v13, v1
	v_mov_b32_e32 v14, v1
	v_mov_b32_e32 v15, v1
	v_mov_b32_e32 v16, v1
	v_mov_b32_e32 v17, v1
	v_mov_b32_e32 v18, v1
	v_mov_b32_e32 v19, v1
	v_mov_b32_e32 v20, v1
	v_mov_b32_e32 v21, v1
	v_mov_b32_e32 v22, v1
	v_mov_b32_e32 v23, v1
	v_mov_b32_e32 v24, v1
	v_mov_b32_e32 v25, v1
	v_mov_b32_e32 v26, v1
	v_mov_b32_e32 v27, v1
	v_mov_b32_e32 v28, v1
	v_mov_b32_e32 v29, v1
	v_mov_b32_e32 v30, v1
	v_mov_b32_e32 v31, v1
	v_lshlrev_b32_e32 v108, 4, v0
	v_mov_b32_e32 v0, v1
	s_waitcnt vmcnt(10)
	v_lshlrev_b32_e32 v143, 1, v32
	s_waitcnt vmcnt(9)
	v_lshlrev_b32_e32 v144, 1, v33
	v_mov_b64_e32 v[32:33], v[30:31]
	s_add_i32 s36, s21, 0xffffffa0
	v_add_u32_e32 v110, 0xffffff80, v106
	v_add_u32_e32 v111, 0xffffff7f, v106
	v_add_u32_e32 v112, 0xffffff7e, v106
	v_add_u32_e32 v113, 0xffffff7d, v106
	v_add_u32_e32 v114, 0xffffff78, v106
	v_add_u32_e32 v115, 0xffffff77, v106
	v_add_u32_e32 v116, 0xffffff76, v106
	v_add_u32_e32 v117, 0xffffff75, v106
	v_add_u32_e32 v118, 0xffffff70, v106
	v_add_u32_e32 v119, 0xffffff6f, v106
	v_add_u32_e32 v120, 0xffffff6e, v106
	v_add_u32_e32 v121, 0xffffff6d, v106
	v_add_u32_e32 v122, 0xffffff68, v106
	v_add_u32_e32 v123, 0xffffff67, v106
	v_add_u32_e32 v124, 0xffffff66, v106
	v_add_u32_e32 v125, 0xffffff65, v106
	v_add_u32_e32 v126, 0xffffff60, v106
	v_add_u32_e32 v127, 0xffffff5f, v106
	v_add_u32_e32 v128, 0xffffff5e, v106
	v_add_u32_e32 v129, 0xffffff5d, v106
	v_add_u32_e32 v130, 0xffffff58, v106
	v_add_u32_e32 v131, 0xffffff57, v106
	v_add_u32_e32 v132, 0xffffff56, v106
	v_add_u32_e32 v133, 0xffffff55, v106
	v_add_u32_e32 v134, 0xffffff50, v106
	v_add_u32_e32 v135, 0xffffff4f, v106
	v_add_u32_e32 v136, 0xffffff4e, v106
	v_add_u32_e32 v137, 0xffffff4d, v106
	v_add_u32_e32 v138, 0xffffff48, v106
	v_add_u32_e32 v139, 0xffffff47, v106
	v_add_u32_e32 v140, 0xffffff46, v106
	v_add_u32_e32 v141, 0xffffff45, v106
	s_lshl_b32 s37, s9, 6
	v_mov_b32_e32 v101, 0
	v_mov_b32_e32 v105, 0xf149f2ca
	s_mov_b32 s98, 1
	v_mov_b32_e32 v212, 0
	v_mov_b32_e32 v213, 0
	v_mov_b32_e32 v214, 0
	v_mov_b32_e32 v215, 0
	v_mov_b32_e32 v216, 0
	v_mov_b32_e32 v217, 0
	v_mov_b32_e32 v218, 0
	v_mov_b32_e32 v219, 0
	v_mov_b32_e32 v220, 0
	v_mov_b32_e32 v221, 0
	v_mov_b32_e32 v222, 0
	v_mov_b32_e32 v223, 0
	v_mov_b32_e32 v224, 0
	v_mov_b32_e32 v225, 0
	v_mov_b32_e32 v226, 0
	v_mov_b32_e32 v227, 0
	v_mov_b32_e32 v228, 0
	v_mov_b32_e32 v229, v105
	v_lshlrev_b32_e32 v142, 1, v34
	v_mov_b64_e32 v[30:31], v[28:29]
	v_mov_b64_e32 v[28:29], v[26:27]
	v_mov_b64_e32 v[26:27], v[24:25]
	v_mov_b64_e32 v[24:25], v[22:23]
	v_mov_b64_e32 v[22:23], v[20:21]
	v_mov_b64_e32 v[20:21], v[18:19]
	v_mov_b64_e32 v[18:19], v[16:17]
	v_mov_b64_e32 v[16:17], v[14:15]
	v_mov_b64_e32 v[14:15], v[12:13]
	v_mov_b64_e32 v[12:13], v[10:11]
	v_mov_b64_e32 v[10:11], v[8:9]
	v_mov_b64_e32 v[8:9], v[6:7]
	v_mov_b64_e32 v[6:7], v[4:5]
	v_mov_b64_e32 v[4:5], v[2:3]
	v_mov_b64_e32 v[2:3], v[0:1]
	s_mov_b32 s38, s9
	s_branch .LBB0_2145
.LBB0_2144:
	v_exp_f32_e32 v0, v50
	v_exp_f32_e32 v51, v51
	v_exp_f32_e32 v52, v52
	v_add_u32_e32 v50, s39, v109
	v_exp_f32_e32 v53, v53
	v_add3_u32 v145, v50, v143, v144
	v_add_f32_e32 v50, 0, v0
	v_exp_f32_e32 v54, v54
	v_add_f32_e32 v50, v51, v50
	v_exp_f32_e32 v55, v55
	v_add_f32_e32 v50, v52, v50
	v_exp_f32_e32 v56, v56
	v_add_f32_e32 v50, v53, v50
	v_exp_f32_e32 v57, v57
	v_add_f32_e32 v50, v54, v50
	v_exp_f32_e32 v58, v58
	v_add_f32_e32 v50, v55, v50
	v_exp_f32_e32 v59, v59
	v_add_f32_e32 v50, v56, v50
	v_exp_f32_e32 v60, v60
	v_add_f32_e32 v50, v57, v50
	v_exp_f32_e32 v61, v61
	v_add_f32_e32 v50, v58, v50
	v_exp_f32_e32 v62, v62
	v_add_f32_e32 v50, v59, v50
	v_exp_f32_e32 v63, v63
	v_add_f32_e32 v50, v60, v50
	v_exp_f32_e32 v64, v64
	v_add_f32_e32 v50, v61, v50
	v_exp_f32_e32 v65, v65
	v_add_f32_e32 v50, v62, v50
	v_exp_f32_e32 v146, v34
	v_add_f32_e32 v34, v63, v50
	v_exp_f32_e32 v147, v35
	v_add_f32_e32 v34, v64, v34
	v_exp_f32_e32 v148, v36
	v_add_f32_e32 v34, v65, v34
	v_exp_f32_e32 v149, v37
	v_add_f32_e32 v34, v146, v34
	v_exp_f32_e32 v150, v38
	v_add_f32_e32 v34, v147, v34
	v_add_f32_e32 v34, v148, v34
	v_add_f32_e32 v34, v149, v34
	v_add_f32_e32 v151, v150, v34
	v_exp_f32_e32 v152, v39
	v_exp_f32_e32 v153, v40
	v_exp_f32_e32 v154, v41
	ds_read_b64_tr_b16 v[34:35], v145 offset:9216
	ds_read_b64_tr_b16 v[36:37], v145 offset:10752
	v_exp_f32_e32 v155, v42
	v_cvt_pk_bf16_f32 v39, v52, v53
	v_cvt_pk_bf16_f32 v38, v0, v51
	ds_read_b64_tr_b16 v[52:53], v145 offset:10816
	ds_read_b64_tr_b16 v[50:51], v145 offset:9280
	v_cvt_pk_bf16_f32 v41, v56, v57
	v_cvt_pk_bf16_f32 v40, v54, v55
	v_mov_b32_e32 v54, v43
	s_waitcnt lgkmcnt(2)
	v_mfma_f32_32x32x16_bf16 v[2:17], v[34:37], v[38:41], v[2:17]
	ds_read_b64_tr_b16 v[34:35], v145 offset:12288
	ds_read_b64_tr_b16 v[36:37], v145 offset:13824
	v_exp_f32_e32 v55, v44
	v_exp_f32_e32 v47, v47
	v_add_f32_e32 v0, v152, v151
	v_add_f32_e32 v0, v153, v0
	v_add_f32_e32 v0, v154, v0
	s_waitcnt lgkmcnt(2)
	v_mfma_f32_32x32x16_bf16 v[18:33], v[50:53], v[38:41], v[18:33]
	ds_read_b64_tr_b16 v[52:53], v145 offset:13888
	ds_read_b64_tr_b16 v[50:51], v145 offset:12352
	v_cvt_pk_bf16_f32 v41, v64, v65
	v_cvt_pk_bf16_f32 v40, v62, v63
	v_cvt_pk_bf16_f32 v39, v60, v61
	v_cvt_pk_bf16_f32 v38, v58, v59
	v_add_f32_e32 v0, v155, v0
	s_add_i32 s37, s37, 64
	s_waitcnt lgkmcnt(2)
	v_mfma_f32_32x32x16_bf16 v[2:17], v[34:37], v[38:41], v[2:17]
	v_exp_f32_e32 v56, v45
	v_exp_f32_e32 v46, v46
	ds_read_b64_tr_b16 v[34:35], v145 offset:15360
	ds_read_b64_tr_b16 v[36:37], v145 offset:16896
	ds_read_b64_tr_b16 v[44:45], v145 offset:16960
	ds_read_b64_tr_b16 v[42:43], v145 offset:15424
	s_cmp_ge_u32 s38, s11
	s_waitcnt lgkmcnt(4)
	v_mfma_f32_32x32x16_bf16 v[18:33], v[50:53], v[38:41], v[18:33]
	v_cvt_pk_bf16_f32 v41, v153, v154
	v_cvt_pk_bf16_f32 v40, v150, v152
	v_cvt_pk_bf16_f32 v39, v148, v149
	v_cvt_pk_bf16_f32 v38, v146, v147
	v_exp_f32_e32 v50, v54
	s_nop 0
	v_add_f32_e32 v0, v50, v0
	s_waitcnt lgkmcnt(2)
	v_mfma_f32_32x32x16_bf16 v[2:17], v[34:37], v[38:41], v[2:17]
	v_exp_f32_e32 v48, v48
	v_exp_f32_e32 v49, v49
	ds_read_b64_tr_b16 v[34:35], v145 offset:18432
	ds_read_b64_tr_b16 v[36:37], v145 offset:19968
	v_add_f32_e32 v0, v55, v0
	v_add_f32_e32 v0, v56, v0
	s_waitcnt lgkmcnt(2)
	v_mfma_f32_32x32x16_bf16 v[18:33], v[42:45], v[38:41], v[18:33]
	ds_read_b64_tr_b16 v[44:45], v145 offset:20032
	ds_read_b64_tr_b16 v[42:43], v145 offset:18496
	v_cvt_pk_bf16_f32 v41, v48, v49
	v_cvt_pk_bf16_f32 v40, v46, v47
	v_cvt_pk_bf16_f32 v39, v55, v56
	v_cvt_pk_bf16_f32 v38, v155, v50
	v_add_f32_e32 v0, v46, v0
	v_add_f32_e32 v0, v47, v0
	s_waitcnt lgkmcnt(2)
	v_mfma_f32_32x32x16_bf16 v[2:17], v[34:37], v[38:41], v[2:17]
	v_add_f32_e32 v0, v48, v0
	v_add_f32_e32 v0, v49, v0
	v_add_f32_e32 v101, v101, v0
	s_waitcnt lgkmcnt(0)
	v_mfma_f32_32x32x16_bf16 v[18:33], v[42:45], v[38:41], v[18:33]
	s_mov_b32 s98, 0
	v_cmp_lt_f32_e32 vcc, 0x49800000, v0
	s_cbranch_vccz .Lsgphase8_21013
	s_nop 7
	s_nop 4
	v_mov_b32_e32 v230, v0
	v_mov_b32_e32 v231, v0
	s_nop 1
	v_permlane32_swap_b32_e32 v230, v231
	v_max_f32_e32 v230, v230, v231
	v_max_f32_e32 v230, 1.0, v230
	v_log_f32_e32 v230, v230
	s_nop 0
	v_sub_f32_e32 v232, 0, v230
	v_exp_f32_e32 v232, v232
	s_nop 0
	v_pk_mul_f32 v[32:33], v[32:33], v[232:233] op_sel_hi:[1,0]
	v_pk_mul_f32 v[30:31], v[30:31], v[232:233] op_sel_hi:[1,0]
	v_pk_mul_f32 v[28:29], v[28:29], v[232:233] op_sel_hi:[1,0]
	v_pk_mul_f32 v[26:27], v[26:27], v[232:233] op_sel_hi:[1,0]
	v_pk_mul_f32 v[24:25], v[24:25], v[232:233] op_sel_hi:[1,0]
	v_pk_mul_f32 v[22:23], v[22:23], v[232:233] op_sel_hi:[1,0]
	v_pk_mul_f32 v[20:21], v[20:21], v[232:233] op_sel_hi:[1,0]
	v_pk_mul_f32 v[18:19], v[18:19], v[232:233] op_sel_hi:[1,0]
	v_pk_mul_f32 v[16:17], v[16:17], v[232:233] op_sel_hi:[1,0]
	v_pk_mul_f32 v[14:15], v[14:15], v[232:233] op_sel_hi:[1,0]
	v_pk_mul_f32 v[12:13], v[12:13], v[232:233] op_sel_hi:[1,0]
	v_pk_mul_f32 v[10:11], v[10:11], v[232:233] op_sel_hi:[1,0]
	v_pk_mul_f32 v[8:9], v[8:9], v[232:233] op_sel_hi:[1,0]
	v_pk_mul_f32 v[6:7], v[6:7], v[232:233] op_sel_hi:[1,0]
	v_pk_mul_f32 v[4:5], v[4:5], v[232:233] op_sel_hi:[1,0]
	v_pk_mul_f32 v[2:3], v[2:3], v[232:233] op_sel_hi:[1,0]
	v_mul_f32_e32 v101, v101, v232
	v_sub_f32_e32 v228, v228, v230
	v_xor_b32_e32 v105, 0x80000000, v228
	v_mov_b32_e32 v212, v228
	v_mov_b32_e32 v213, v228
	v_mov_b32_e32 v214, v228
	v_mov_b32_e32 v215, v228
	v_mov_b32_e32 v216, v228
	v_mov_b32_e32 v217, v228
	v_mov_b32_e32 v218, v228
	v_mov_b32_e32 v219, v228
	v_mov_b32_e32 v220, v228
	v_mov_b32_e32 v221, v228
	v_mov_b32_e32 v222, v228
	v_mov_b32_e32 v223, v228
	v_mov_b32_e32 v224, v228
	v_mov_b32_e32 v225, v228
	v_mov_b32_e32 v226, v228
	v_mov_b32_e32 v227, v228
.Lsgphase8_21013:
	s_cbranch_scc1 .LBB0_2152
.LBB0_2145:
	s_add_i32 s2, s10, s38
	s_bitcmp1_b32 s2, 0
	s_cselect_b32 s39, 0x5400, 0
	v_add3_u32 v0, s39, v102, v104
	s_add_i32 s38, s38, 1
	s_waitcnt vmcnt(1)
	ds_write_b128 v0, v[66:69]
	v_add3_u32 v0, s39, v103, v104
	s_cmp_ge_u32 s38, s8
	s_waitcnt vmcnt(0)
	ds_write_b128 v0, v[70:73] offset:9216
	s_cbranch_scc1 .LBB0_2147
	s_add_i32 s14, s37, 64
	s_lshl_b64 s[2:3], s[14:15], 8
	v_lshl_add_u64 v[36:37], v[94:95], 0, s[2:3]
	v_lshl_add_u64 v[34:35], v[96:97], 0, s[2:3]
	global_load_dwordx4 v[66:69], v[36:37], off
	global_load_dwordx4 v[70:73], v[34:35], off

.LBB0_2149:
	s_nop 8
	s_cmp_eq_u32 s98, 0
	s_cbranch_scc1 .LBB0_2144
	v_max3_f32 v0, v50, s30, v51
	v_max3_f32 v0, v0, v52, v53
	v_max3_f32 v0, v0, v54, v55
	v_max3_f32 v0, v0, v56, v57
	v_max3_f32 v0, v0, v58, v59
	v_max3_f32 v0, v0, v60, v61
	v_max3_f32 v0, v0, v62, v63
	v_max3_f32 v0, v0, v64, v65
	v_max3_f32 v0, v0, v34, v35
	v_max3_f32 v0, v0, v36, v37
	v_max3_f32 v0, v0, v38, v39
	v_max3_f32 v0, v0, v40, v41
	v_max3_f32 v0, v0, v42, v43
	v_max3_f32 v0, v0, v44, v45
	v_max3_f32 v0, v0, v46, v47
	v_max3_f32 v0, v0, v48, v49
	ds_bpermute_b32 v145, v98, v0
	s_waitcnt lgkmcnt(0)
	v_max_f32_e32 v145, v145, v145
	v_max_f32_e32 v0, v0, v145
	v_add_f32_e32 v145, 0x41000000, v229
	v_cmp_gt_f32_e32 vcc, v0, v145
	s_cbranch_vccz .LBB0_2144
	v_max_f32_e32 v0, v0, v0
	v_max_f32_e32 v230, v229, v229
	v_max_f32_e32 v230, v230, v0
	v_sub_f32_e32 v231, v230, v228
	v_sub_f32_e32 v0, v229, v230
	v_exp_f32_e32 v0, v0
	s_nop 0
	v_pk_mul_f32 v[32:33], v[32:33], v[0:1] op_sel_hi:[1,0]
	v_pk_mul_f32 v[30:31], v[30:31], v[0:1] op_sel_hi:[1,0]
	v_pk_mul_f32 v[28:29], v[28:29], v[0:1] op_sel_hi:[1,0]
	v_pk_mul_f32 v[26:27], v[26:27], v[0:1] op_sel_hi:[1,0]
	v_pk_mul_f32 v[24:25], v[24:25], v[0:1] op_sel_hi:[1,0]
	v_pk_mul_f32 v[22:23], v[22:23], v[0:1] op_sel_hi:[1,0]
	v_pk_mul_f32 v[20:21], v[20:21], v[0:1] op_sel_hi:[1,0]
	v_pk_mul_f32 v[18:19], v[18:19], v[0:1] op_sel_hi:[1,0]
	v_pk_mul_f32 v[16:17], v[16:17], v[0:1] op_sel_hi:[1,0]
	v_pk_mul_f32 v[14:15], v[14:15], v[0:1] op_sel_hi:[1,0]
	v_pk_mul_f32 v[12:13], v[12:13], v[0:1] op_sel_hi:[1,0]
	v_pk_mul_f32 v[10:11], v[10:11], v[0:1] op_sel_hi:[1,0]
	v_pk_mul_f32 v[8:9], v[8:9], v[0:1] op_sel_hi:[1,0]
	v_pk_mul_f32 v[6:7], v[6:7], v[0:1] op_sel_hi:[1,0]
	v_pk_mul_f32 v[4:5], v[4:5], v[0:1] op_sel_hi:[1,0]
	v_pk_mul_f32 v[2:3], v[2:3], v[0:1] op_sel_hi:[1,0]
	v_mul_f32_e32 v101, v101, v0
	v_mov_b32_e32 v105, v231
	v_xor_b32_e32 v230, 0x80000000, v231
	v_cmp_lt_f32_e32 vcc, 0xf0a18f08, v231
	s_nop 1
	v_cndmask_b32_e32 v230, 0, v230, vcc
	v_add_f32_e32 v229, v231, v230
	v_sub_f32_e32 v231, v230, v228
	v_mov_b32_e32 v228, v230
	v_add_f32_e32 v34, v231, v34
	v_add_f32_e32 v35, v231, v35
	v_add_f32_e32 v36, v231, v36
	v_add_f32_e32 v37, v231, v37
	v_add_f32_e32 v38, v231, v38
	v_add_f32_e32 v39, v231, v39
	v_add_f32_e32 v40, v231, v40
	v_add_f32_e32 v41, v231, v41
	v_add_f32_e32 v42, v231, v42
	v_add_f32_e32 v43, v231, v43
	v_add_f32_e32 v44, v231, v44
	v_add_f32_e32 v45, v231, v45
	v_add_f32_e32 v46, v231, v46
	v_add_f32_e32 v47, v231, v47
	v_add_f32_e32 v48, v231, v48
	v_add_f32_e32 v49, v231, v49
	v_add_f32_e32 v50, v231, v50
	v_add_f32_e32 v51, v231, v51
	v_add_f32_e32 v52, v231, v52
	v_add_f32_e32 v53, v231, v53
	v_add_f32_e32 v54, v231, v54
	v_add_f32_e32 v55, v231, v55
	v_add_f32_e32 v56, v231, v56
	v_add_f32_e32 v57, v231, v57
	v_add_f32_e32 v58, v231, v58
	v_add_f32_e32 v59, v231, v59
	v_add_f32_e32 v60, v231, v60
	v_add_f32_e32 v61, v231, v61
	v_add_f32_e32 v62, v231, v62
	v_add_f32_e32 v63, v231, v63
	v_add_f32_e32 v64, v231, v64
	v_add_f32_e32 v65, v231, v65
	v_mov_b32_e32 v212, v230
	v_mov_b32_e32 v213, v230
	v_mov_b32_e32 v214, v230
	v_mov_b32_e32 v215, v230
	v_mov_b32_e32 v216, v230
	v_mov_b32_e32 v217, v230
	v_mov_b32_e32 v218, v230
	v_mov_b32_e32 v219, v230
	v_mov_b32_e32 v220, v230
	v_mov_b32_e32 v221, v230
	v_mov_b32_e32 v222, v230
	v_mov_b32_e32 v223, v230
	v_mov_b32_e32 v224, v230
	v_mov_b32_e32 v225, v230
	v_mov_b32_e32 v226, v230
	v_mov_b32_e32 v227, v230
	v_cndmask_b32_e32 v105, 0, v105, vcc
	s_branch .LBB0_2144

.LBB0_4401:
	s_lshr_b32 s2, s49, 26
	s_add_i32 s2, s2, s48
	s_add_i32 s2, s2, 31
	s_ashr_i32 s2, s2, 6
	s_add_i32 s2, s2, 1
	s_min_i32 s2, s2, s8
	s_max_i32 s5, s2, s6
	s_cmp_le_i32 s2, s6
	v_mov_b32_e32 v127, 0
	s_cbranch_scc1 .LBB0_4410
	v_bfe_u32 v2, v0, 5, 1
	v_and_b32_e32 v3, 31, v0
	v_lshlrev_b32_e32 v194, 2, v2
	v_lshrrev_b32_e32 v4, 2, v0
	v_and_b32_e32 v96, 16, v0
	v_lshlrev_b32_e32 v0, 2, v0
	v_and_or_b32 v4, v4, 3, v194
	v_and_b32_e32 v97, 12, v0
	v_mul_u32_u24_e32 v98, 0x48, v3
	v_mov_b32_e32 v30, v1
	v_mov_b32_e32 v31, v1
	v_or_b32_e32 v193, s48, v3
	v_lshlrev_b32_e32 v195, 4, v2
	v_mul_u32_u24_e32 v196, 0xc0, v4
	v_mov_b32_e32 v0, v1
	v_mov_b32_e32 v2, v1
	v_mov_b32_e32 v3, v1
	v_mov_b32_e32 v4, v1
	v_mov_b32_e32 v5, v1
	v_mov_b32_e32 v6, v1
	v_mov_b32_e32 v7, v1
	v_mov_b32_e32 v8, v1
	v_mov_b32_e32 v9, v1
	v_mov_b32_e32 v10, v1
	v_mov_b32_e32 v11, v1
	v_mov_b32_e32 v12, v1
	v_mov_b32_e32 v13, v1
	v_mov_b32_e32 v14, v1
	v_mov_b32_e32 v15, v1
	v_mov_b32_e32 v16, v1
	v_mov_b32_e32 v17, v1
	v_mov_b32_e32 v18, v1
	v_mov_b32_e32 v19, v1
	v_mov_b32_e32 v20, v1
	v_mov_b32_e32 v21, v1
	v_mov_b32_e32 v22, v1
	v_mov_b32_e32 v23, v1
	v_mov_b32_e32 v24, v1
	v_mov_b32_e32 v25, v1
	v_mov_b32_e32 v26, v1
	v_mov_b32_e32 v27, v1
	v_mov_b32_e32 v28, v1
	v_mov_b32_e32 v29, v1
	v_lshlrev_b32_e32 v197, 1, v98
	v_lshlrev_b32_e32 v198, 1, v96
	v_lshlrev_b32_e32 v199, 1, v97
	s_waitcnt vmcnt(2)
	v_mov_b64_e32 v[126:127], v[30:31]
	s_add_i32 s7, s48, 0xfffffe20
	s_lshl_b32 s9, s6, 6
	s_sub_i32 s10, 0, s4
	v_mov_b32_e32 v192, 0
	v_mov_b32_e32 v200, 0xf149f2ca
	s_mov_b32 s98, 1
	v_mov_b32_e32 v212, 0
	v_mov_b32_e32 v213, 0
	v_mov_b32_e32 v214, 0
	v_mov_b32_e32 v215, 0
	v_mov_b32_e32 v216, 0
	v_mov_b32_e32 v217, 0
	v_mov_b32_e32 v218, 0
	v_mov_b32_e32 v219, 0
	v_mov_b32_e32 v220, 0
	v_mov_b32_e32 v221, 0
	v_mov_b32_e32 v222, 0
	v_mov_b32_e32 v223, 0
	v_mov_b32_e32 v224, 0
	v_mov_b32_e32 v225, 0
	v_mov_b32_e32 v226, 0
	v_mov_b32_e32 v227, 0
	v_mov_b32_e32 v228, 0
	v_mov_b32_e32 v229, v200
	v_mov_b64_e32 v[124:125], v[28:29]
	v_mov_b64_e32 v[122:123], v[26:27]
	v_mov_b64_e32 v[120:121], v[24:25]
	v_mov_b64_e32 v[118:119], v[22:23]
	v_mov_b64_e32 v[116:117], v[20:21]
	v_mov_b64_e32 v[114:115], v[18:19]
	v_mov_b64_e32 v[112:113], v[16:17]
	v_mov_b64_e32 v[110:111], v[14:15]
	v_mov_b64_e32 v[108:109], v[12:13]
	v_mov_b64_e32 v[106:107], v[10:11]
	v_mov_b64_e32 v[104:105], v[8:9]
	v_mov_b64_e32 v[102:103], v[6:7]
	v_mov_b64_e32 v[100:101], v[4:5]
	v_mov_b64_e32 v[98:99], v[2:3]
	v_mov_b64_e32 v[96:97], v[0:1]
	s_branch .LBB0_4404
.LBB0_4403:
	v_exp_f32_e32 v0, v128
	v_exp_f32_e32 v19, v129
	v_exp_f32_e32 v20, v130
	v_add_u32_e32 v18, s11, v196
	v_exp_f32_e32 v21, v131
	v_add3_u32 v22, v18, v198, v199
	v_add_f32_e32 v18, 0, v0
	v_exp_f32_e32 v23, v132
	v_add_f32_e32 v18, v19, v18
	v_exp_f32_e32 v24, v133
	v_add_f32_e32 v18, v20, v18
	v_exp_f32_e32 v25, v134
	v_add_f32_e32 v18, v21, v18
	v_exp_f32_e32 v26, v135
	v_add_f32_e32 v18, v23, v18
	v_exp_f32_e32 v27, v136
	v_add_f32_e32 v18, v24, v18
	v_exp_f32_e32 v28, v137
	v_add_f32_e32 v18, v25, v18
	v_exp_f32_e32 v29, v138
	v_add_f32_e32 v18, v26, v18
	v_exp_f32_e32 v30, v139
	v_add_f32_e32 v18, v27, v18
	v_exp_f32_e32 v31, v140
	v_add_f32_e32 v18, v28, v18
	v_exp_f32_e32 v128, v141
	v_add_f32_e32 v18, v29, v18
	v_exp_f32_e32 v129, v142
	v_add_f32_e32 v18, v30, v18
	v_exp_f32_e32 v130, v143
	v_add_f32_e32 v18, v31, v18
	v_exp_f32_e32 v131, v2
	v_add_f32_e32 v2, v128, v18
	v_exp_f32_e32 v132, v3
	v_add_f32_e32 v2, v129, v2
	v_exp_f32_e32 v133, v4
	v_add_f32_e32 v2, v130, v2
	v_exp_f32_e32 v134, v5
	v_add_f32_e32 v2, v131, v2
	v_exp_f32_e32 v135, v6
	v_add_f32_e32 v2, v132, v2
	v_add_f32_e32 v2, v133, v2
	v_add_f32_e32 v2, v134, v2
	v_add_f32_e32 v136, v135, v2
	v_exp_f32_e32 v137, v7
	v_exp_f32_e32 v138, v8
	v_exp_f32_e32 v139, v9
	ds_read_b64_tr_b16 v[2:3], v22 offset:9216
	ds_read_b64_tr_b16 v[4:5], v22 offset:10752
	v_exp_f32_e32 v140, v10
	v_cvt_pk_bf16_f32 v7, v20, v21
	v_cvt_pk_bf16_f32 v6, v0, v19
	ds_read_b64_tr_b16 v[20:21], v22 offset:10816
	ds_read_b64_tr_b16 v[18:19], v22 offset:9280
	v_cvt_pk_bf16_f32 v9, v25, v26
	v_cvt_pk_bf16_f32 v8, v23, v24
	v_mov_b32_e32 v23, v11
	s_waitcnt lgkmcnt(2)
	v_mfma_f32_32x32x16_bf16 v[96:111], v[2:5], v[6:9], v[96:111]
	ds_read_b64_tr_b16 v[2:3], v22 offset:12288
	ds_read_b64_tr_b16 v[4:5], v22 offset:13824
	v_exp_f32_e32 v24, v12
	v_exp_f32_e32 v15, v15
	v_add_f32_e32 v0, v137, v136
	v_add_f32_e32 v0, v138, v0
	v_add_f32_e32 v0, v139, v0
	s_waitcnt lgkmcnt(2)
	v_mfma_f32_32x32x16_bf16 v[112:127], v[18:21], v[6:9], v[112:127]
	ds_read_b64_tr_b16 v[20:21], v22 offset:13888
	ds_read_b64_tr_b16 v[18:19], v22 offset:12352
	v_cvt_pk_bf16_f32 v9, v129, v130
	v_cvt_pk_bf16_f32 v8, v31, v128
	v_cvt_pk_bf16_f32 v7, v29, v30
	v_cvt_pk_bf16_f32 v6, v27, v28
	v_add_f32_e32 v0, v140, v0
	s_add_i32 s9, s9, 64
	s_waitcnt lgkmcnt(2)
	v_mfma_f32_32x32x16_bf16 v[96:111], v[2:5], v[6:9], v[96:111]
	v_exp_f32_e32 v25, v13
	v_exp_f32_e32 v14, v14
	ds_read_b64_tr_b16 v[2:3], v22 offset:15360
	ds_read_b64_tr_b16 v[4:5], v22 offset:16896
	ds_read_b64_tr_b16 v[12:13], v22 offset:16960
	ds_read_b64_tr_b16 v[10:11], v22 offset:15424
	s_cmp_ge_u32 s6, s5
	s_waitcnt lgkmcnt(4)
	v_mfma_f32_32x32x16_bf16 v[112:127], v[18:21], v[6:9], v[112:127]
	v_cvt_pk_bf16_f32 v9, v138, v139
	v_cvt_pk_bf16_f32 v8, v135, v137
	v_cvt_pk_bf16_f32 v7, v133, v134
	v_cvt_pk_bf16_f32 v6, v131, v132
	v_exp_f32_e32 v18, v23
	s_nop 0
	v_add_f32_e32 v0, v18, v0
	s_waitcnt lgkmcnt(2)
	v_mfma_f32_32x32x16_bf16 v[96:111], v[2:5], v[6:9], v[96:111]
	v_exp_f32_e32 v16, v16
	v_exp_f32_e32 v17, v17
	ds_read_b64_tr_b16 v[2:3], v22 offset:18432
	ds_read_b64_tr_b16 v[4:5], v22 offset:19968
	v_add_f32_e32 v0, v24, v0
	v_add_f32_e32 v0, v25, v0
	s_waitcnt lgkmcnt(2)
	v_mfma_f32_32x32x16_bf16 v[112:127], v[10:13], v[6:9], v[112:127]
	ds_read_b64_tr_b16 v[12:13], v22 offset:20032
	ds_read_b64_tr_b16 v[10:11], v22 offset:18496
	v_cvt_pk_bf16_f32 v9, v16, v17
	v_cvt_pk_bf16_f32 v8, v14, v15
	v_cvt_pk_bf16_f32 v7, v24, v25
	v_cvt_pk_bf16_f32 v6, v140, v18
	v_add_f32_e32 v0, v14, v0
	v_add_f32_e32 v0, v15, v0
	s_waitcnt lgkmcnt(2)
	v_mfma_f32_32x32x16_bf16 v[96:111], v[2:5], v[6:9], v[96:111]
	v_add_f32_e32 v0, v16, v0
	v_add_f32_e32 v0, v17, v0
	v_add_f32_e32 v192, v192, v0
	s_waitcnt lgkmcnt(0)
	v_mfma_f32_32x32x16_bf16 v[112:127], v[10:13], v[6:9], v[112:127]
	s_mov_b32 s98, 0
	v_cmp_lt_f32_e32 vcc, 0x49800000, v0
	s_cbranch_vccz .Lsgphase15_36571
	s_nop 7
	s_nop 4
	v_mov_b32_e32 v230, v0
	v_mov_b32_e32 v231, v0
	s_nop 1
	v_permlane32_swap_b32_e32 v230, v231
	v_max_f32_e32 v230, v230, v231
	v_max_f32_e32 v230, 1.0, v230
	v_log_f32_e32 v230, v230
	s_nop 0
	v_sub_f32_e32 v232, 0, v230
	v_exp_f32_e32 v232, v232
	s_nop 0
	v_pk_mul_f32 v[126:127], v[126:127], v[232:233] op_sel_hi:[1,0]
	v_pk_mul_f32 v[124:125], v[124:125], v[232:233] op_sel_hi:[1,0]
	v_pk_mul_f32 v[122:123], v[122:123], v[232:233] op_sel_hi:[1,0]
	v_pk_mul_f32 v[120:121], v[120:121], v[232:233] op_sel_hi:[1,0]
	v_pk_mul_f32 v[118:119], v[118:119], v[232:233] op_sel_hi:[1,0]
	v_pk_mul_f32 v[116:117], v[116:117], v[232:233] op_sel_hi:[1,0]
	v_pk_mul_f32 v[114:115], v[114:115], v[232:233] op_sel_hi:[1,0]
	v_pk_mul_f32 v[112:113], v[112:113], v[232:233] op_sel_hi:[1,0]
	v_pk_mul_f32 v[110:111], v[110:111], v[232:233] op_sel_hi:[1,0]
	v_pk_mul_f32 v[108:109], v[108:109], v[232:233] op_sel_hi:[1,0]
	v_pk_mul_f32 v[106:107], v[106:107], v[232:233] op_sel_hi:[1,0]
	v_pk_mul_f32 v[104:105], v[104:105], v[232:233] op_sel_hi:[1,0]
	v_pk_mul_f32 v[102:103], v[102:103], v[232:233] op_sel_hi:[1,0]
	v_pk_mul_f32 v[100:101], v[100:101], v[232:233] op_sel_hi:[1,0]
	v_pk_mul_f32 v[98:99], v[98:99], v[232:233] op_sel_hi:[1,0]
	v_pk_mul_f32 v[96:97], v[96:97], v[232:233] op_sel_hi:[1,0]
	v_mul_f32_e32 v192, v192, v232
	v_sub_f32_e32 v228, v228, v230
	v_xor_b32_e32 v200, 0x80000000, v228
	v_mov_b32_e32 v212, v228
	v_mov_b32_e32 v213, v228
	v_mov_b32_e32 v214, v228
	v_mov_b32_e32 v215, v228
	v_mov_b32_e32 v216, v228
	v_mov_b32_e32 v217, v228
	v_mov_b32_e32 v218, v228
	v_mov_b32_e32 v219, v228
	v_mov_b32_e32 v220, v228
	v_mov_b32_e32 v221, v228
	v_mov_b32_e32 v222, v228
	v_mov_b32_e32 v223, v228
	v_mov_b32_e32 v224, v228
	v_mov_b32_e32 v225, v228
	v_mov_b32_e32 v226, v228
	v_mov_b32_e32 v227, v228
.Lsgphase15_36571:
	s_cbranch_scc1 .LBB0_4411
.LBB0_4404:
	s_add_i32 s2, s10, s6
	s_bitcmp1_b32 s2, 0
	s_cselect_b32 s11, 0x5400, 0
	v_lshlrev_b32_e32 v0, 1, v176
	s_add_i32 s6, s6, 1
	v_add3_u32 v2, s11, v190, v0
	v_add3_u32 v0, s11, v191, v0
	s_cmp_ge_i32 s6, s8
	s_waitcnt vmcnt(1)
	ds_write_b128 v2, v[160:163]
	s_waitcnt vmcnt(0)
	ds_write_b128 v0, v[164:167] offset:9216
	s_cbranch_scc1 .LBB0_4406
	s_add_i32 s20, s9, 64
	s_lshl_b64 s[2:3], s[20:21], 9
	v_lshl_add_u64 v[4:5], v[178:179], 0, s[2:3]
	v_lshl_add_u64 v[2:3], v[180:181], 0, s[2:3]
	global_load_dwordx4 v[160:163], v[4:5], off
	global_load_dwordx4 v[164:167], v[2:3], off

.LBB0_4408:
	s_nop 8
	s_cmp_eq_u32 s98, 0
	s_cbranch_scc1 .LBB0_4403
	v_max3_f32 v0, v128, s66, v129
	v_max3_f32 v0, v0, v130, v131
	v_max3_f32 v0, v0, v132, v133
	v_max3_f32 v0, v0, v134, v135
	v_max3_f32 v0, v0, v136, v137
	v_max3_f32 v0, v0, v138, v139
	v_max3_f32 v0, v0, v140, v141
	v_max3_f32 v0, v0, v142, v143
	v_max3_f32 v0, v0, v2, v3
	v_max3_f32 v0, v0, v4, v5
	v_max3_f32 v0, v0, v6, v7
	v_max3_f32 v0, v0, v8, v9
	v_max3_f32 v0, v0, v10, v11
	v_max3_f32 v0, v0, v12, v13
	v_max3_f32 v0, v0, v14, v15
	v_max3_f32 v0, v0, v16, v17
	ds_bpermute_b32 v18, v175, v0
	s_waitcnt lgkmcnt(0)
	v_max_f32_e32 v18, v18, v18
	v_max_f32_e32 v0, v0, v18
	v_add_f32_e32 v18, 0x41000000, v229
	v_cmp_gt_f32_e32 vcc, v0, v18
	s_cbranch_vccz .LBB0_4403
	v_max_f32_e32 v0, v0, v0
	v_max_f32_e32 v230, v229, v229
	v_max_f32_e32 v230, v230, v0
	v_sub_f32_e32 v231, v230, v228
	v_sub_f32_e32 v0, v229, v230
	v_exp_f32_e32 v0, v0
	s_nop 0
	v_pk_mul_f32 v[126:127], v[126:127], v[0:1] op_sel_hi:[1,0]
	v_pk_mul_f32 v[124:125], v[124:125], v[0:1] op_sel_hi:[1,0]
	v_pk_mul_f32 v[122:123], v[122:123], v[0:1] op_sel_hi:[1,0]
	v_pk_mul_f32 v[120:121], v[120:121], v[0:1] op_sel_hi:[1,0]
	v_pk_mul_f32 v[118:119], v[118:119], v[0:1] op_sel_hi:[1,0]
	v_pk_mul_f32 v[116:117], v[116:117], v[0:1] op_sel_hi:[1,0]
	v_pk_mul_f32 v[114:115], v[114:115], v[0:1] op_sel_hi:[1,0]
	v_pk_mul_f32 v[112:113], v[112:113], v[0:1] op_sel_hi:[1,0]
	v_pk_mul_f32 v[110:111], v[110:111], v[0:1] op_sel_hi:[1,0]
	v_pk_mul_f32 v[108:109], v[108:109], v[0:1] op_sel_hi:[1,0]
	v_pk_mul_f32 v[106:107], v[106:107], v[0:1] op_sel_hi:[1,0]
	v_pk_mul_f32 v[104:105], v[104:105], v[0:1] op_sel_hi:[1,0]
	v_pk_mul_f32 v[102:103], v[102:103], v[0:1] op_sel_hi:[1,0]
	v_pk_mul_f32 v[100:101], v[100:101], v[0:1] op_sel_hi:[1,0]
	v_pk_mul_f32 v[98:99], v[98:99], v[0:1] op_sel_hi:[1,0]
	v_pk_mul_f32 v[96:97], v[96:97], v[0:1] op_sel_hi:[1,0]
	v_mul_f32_e32 v192, v192, v0
	v_mov_b32_e32 v200, v231
	v_xor_b32_e32 v230, 0x80000000, v231
	v_cmp_lt_f32_e32 vcc, 0xf0a18f08, v231
	s_nop 1
	v_cndmask_b32_e32 v230, 0, v230, vcc
	v_add_f32_e32 v229, v231, v230
	v_sub_f32_e32 v231, v230, v228
	v_mov_b32_e32 v228, v230
	v_add_f32_e32 v2, v231, v2
	v_add_f32_e32 v3, v231, v3
	v_add_f32_e32 v4, v231, v4
	v_add_f32_e32 v5, v231, v5
	v_add_f32_e32 v6, v231, v6
	v_add_f32_e32 v7, v231, v7
	v_add_f32_e32 v8, v231, v8
	v_add_f32_e32 v9, v231, v9
	v_add_f32_e32 v10, v231, v10
	v_add_f32_e32 v11, v231, v11
	v_add_f32_e32 v12, v231, v12
	v_add_f32_e32 v13, v231, v13
	v_add_f32_e32 v14, v231, v14
	v_add_f32_e32 v15, v231, v15
	v_add_f32_e32 v16, v231, v16
	v_add_f32_e32 v17, v231, v17
	v_add_f32_e32 v128, v231, v128
	v_add_f32_e32 v129, v231, v129
	v_add_f32_e32 v130, v231, v130
	v_add_f32_e32 v131, v231, v131
	v_add_f32_e32 v132, v231, v132
	v_add_f32_e32 v133, v231, v133
	v_add_f32_e32 v134, v231, v134
	v_add_f32_e32 v135, v231, v135
	v_add_f32_e32 v136, v231, v136
	v_add_f32_e32 v137, v231, v137
	v_add_f32_e32 v138, v231, v138
	v_add_f32_e32 v139, v231, v139
	v_add_f32_e32 v140, v231, v140
	v_add_f32_e32 v141, v231, v141
	v_add_f32_e32 v142, v231, v142
	v_add_f32_e32 v143, v231, v143
	v_mov_b32_e32 v212, v230
	v_mov_b32_e32 v213, v230
	v_mov_b32_e32 v214, v230
	v_mov_b32_e32 v215, v230
	v_mov_b32_e32 v216, v230
	v_mov_b32_e32 v217, v230
	v_mov_b32_e32 v218, v230
	v_mov_b32_e32 v219, v230
	v_mov_b32_e32 v220, v230
	v_mov_b32_e32 v221, v230
	v_mov_b32_e32 v222, v230
	v_mov_b32_e32 v223, v230
	v_mov_b32_e32 v224, v230
	v_mov_b32_e32 v225, v230
	v_mov_b32_e32 v226, v230
	v_mov_b32_e32 v227, v230
	v_cndmask_b32_e32 v200, 0, v200, vcc
	s_branch .LBB0_4403
